# v22 + nt hint on the MoE hidden-activation (H2) stores of the expert up-projection epilogue
# speedup vs baseline: 1.0028x; 1.0028x over previous
.LBB0_1275:
	v_pk_mul_f32 v[0:1], v[156:157], s[10:11] op_sel_hi:[1,0]
	v_pk_mul_f32 v[6:7], v[158:159], s[10:11] op_sel_hi:[1,0]
	v_exp_f32_e32 v2, v0
	v_exp_f32_e32 v3, v1
	v_exp_f32_e32 v6, v6
	v_exp_f32_e32 v7, v7
	v_pk_mul_f32 v[10:11], v[156:157], v[152:153]
	v_pk_add_f32 v[2:3], v[2:3], 1.0 op_sel_hi:[1,0]
	v_pk_mul_f32 v[8:9], v[158:159], v[154:155]
	v_rcp_f32_e32 v2, v2
	v_rcp_f32_e32 v3, v3
	v_pk_add_f32 v[6:7], v[6:7], 1.0 op_sel_hi:[1,0]
	v_pk_mul_f32 v[14:15], v[148:149], v[144:145]
	v_rcp_f32_e32 v6, v6
	v_pk_mul_f32 v[2:3], v[2:3], v[10:11]
	v_pk_mul_f32 v[10:11], v[148:149], s[10:11] op_sel_hi:[1,0]
	v_rcp_f32_e32 v7, v7
	v_exp_f32_e32 v10, v10
	v_exp_f32_e32 v11, v11
	v_pk_mul_f32 v[2:3], v[2:3], s[12:13] op_sel_hi:[1,0]
	v_pk_mul_f32 v[6:7], v[6:7], v[8:9]
	v_pk_mul_f32 v[12:13], v[150:151], v[146:147]
	v_pk_add_f32 v[8:9], v[10:11], 1.0 op_sel_hi:[1,0]
	v_pk_mul_f32 v[10:11], v[150:151], s[10:11] op_sel_hi:[1,0]
	v_rcp_f32_e32 v8, v8
	v_exp_f32_e32 v10, v10
	v_exp_f32_e32 v11, v11
	v_rcp_f32_e32 v9, v9
	v_pk_mul_f32 v[6:7], v[6:7], s[12:13] op_sel_hi:[1,0]
	v_med3_f32 v2, v2, s52, v184
	v_pk_add_f32 v[10:11], v[10:11], 1.0 op_sel_hi:[1,0]
	v_pk_mul_f32 v[8:9], v[8:9], v[14:15]
	v_rcp_f32_e32 v10, v10
	v_rcp_f32_e32 v11, v11
	v_pk_mul_f32 v[8:9], v[8:9], s[12:13] op_sel_hi:[1,0]
	v_med3_f32 v3, v3, s52, v184
	s_mul_hi_i32 s15, s26, 0x92492493
	v_pk_mul_f32 v[10:11], v[10:11], v[12:13]
	v_mov_b32_e32 v12, v165
	v_cvt_pk_fp8_f32 v12, v2, v3
	v_med3_f32 v2, v6, s52, v184
	v_med3_f32 v5, v8, s52, v184
	v_med3_f32 v6, v9, s52, v184
	v_mov_b32_e32 v13, v165
	s_add_i32 s15, s15, s26
	v_cvt_pk_fp8_f32 v13, v5, v6
	s_lshr_b32 s17, s15, 31
	s_lshr_b32 s15, s15, 4
	s_add_i32 s15, s15, s17
	v_pk_mul_f32 v[10:11], v[10:11], s[12:13] op_sel_hi:[1,0]
	v_med3_f32 v3, v7, s52, v184
	s_mul_i32 s15, s15, 28
	v_cvt_pk_fp8_f32 v12, v2, v3 op_sel:[0,0,1]
	v_med3_f32 v2, v10, s52, v184
	v_med3_f32 v3, v11, s52, v184
	v_pk_mul_f32 v[6:7], v[140:141], s[10:11] op_sel_hi:[1,0]
	s_sub_i32 s15, s26, s15
	v_cvt_pk_fp8_f32 v13, v2, v3 op_sel:[0,0,1]
	v_exp_f32_e32 v6, v6
	v_exp_f32_e32 v7, v7
	v_lshl_add_u32 v4, s24, 8, v180
	v_lshl_or_b32 v0, s15, 7, v181
	v_mov_b64_e32 v[2:3], s[58:59]
	v_ashrrev_i32_e32 v1, 31, v0
	v_mad_i64_i32 v[8:9], s[28:29], v4, s53, v[2:3]
	v_lshl_add_u64 v[8:9], v[8:9], 0, v[0:1]
	global_store_dwordx2 v[8:9], v[12:13], off nt
	v_pk_add_f32 v[6:7], v[6:7], 1.0 op_sel_hi:[1,0]
	v_pk_mul_f32 v[8:9], v[142:143], s[10:11] op_sel_hi:[1,0]
	v_rcp_f32_e32 v6, v6
	v_rcp_f32_e32 v7, v7
	v_exp_f32_e32 v8, v8
	v_exp_f32_e32 v9, v9
	v_pk_mul_f32 v[12:13], v[140:141], v[136:137]
	v_pk_mul_f32 v[10:11], v[142:143], v[138:139]
	v_pk_mul_f32 v[6:7], v[6:7], v[12:13]
	v_pk_add_f32 v[8:9], v[8:9], 1.0 op_sel_hi:[1,0]
	v_pk_mul_f32 v[12:13], v[132:133], s[10:11] op_sel_hi:[1,0]
	v_rcp_f32_e32 v8, v8
	v_rcp_f32_e32 v9, v9
	v_exp_f32_e32 v12, v12
	v_exp_f32_e32 v13, v13
	v_pk_mul_f32 v[16:17], v[132:133], v[128:129]
	v_pk_mul_f32 v[8:9], v[8:9], v[10:11]
	v_pk_mul_f32 v[6:7], v[6:7], s[12:13] op_sel_hi:[1,0]
	v_pk_add_f32 v[10:11], v[12:13], 1.0 op_sel_hi:[1,0]
	v_pk_mul_f32 v[12:13], v[134:135], s[10:11] op_sel_hi:[1,0]
	v_rcp_f32_e32 v10, v10
	v_exp_f32_e32 v12, v12
	v_exp_f32_e32 v13, v13
	v_rcp_f32_e32 v11, v11
	v_pk_mul_f32 v[8:9], v[8:9], s[12:13] op_sel_hi:[1,0]
	v_med3_f32 v5, v6, s52, v184
	v_pk_add_f32 v[12:13], v[12:13], 1.0 op_sel_hi:[1,0]
	v_pk_mul_f32 v[10:11], v[10:11], v[16:17]
	v_rcp_f32_e32 v12, v12
	v_rcp_f32_e32 v13, v13
	v_pk_mul_f32 v[10:11], v[10:11], s[12:13] op_sel_hi:[1,0]
	v_med3_f32 v7, v7, s52, v184
	v_mov_b32_e32 v6, v165
	v_cvt_pk_fp8_f32 v6, v5, v7
	v_med3_f32 v5, v8, s52, v184
	v_med3_f32 v8, v9, s52, v184
	v_med3_f32 v9, v10, s52, v184
	v_med3_f32 v10, v11, s52, v184
	v_mov_b32_e32 v7, v165
	v_pk_mul_f32 v[14:15], v[134:135], v[130:131]
	v_cvt_pk_fp8_f32 v7, v9, v10
	v_pk_mul_f32 v[12:13], v[12:13], v[14:15]
	v_cvt_pk_fp8_f32 v6, v5, v8 op_sel:[0,0,1]
	v_pk_mul_f32 v[12:13], v[12:13], s[12:13] op_sel_hi:[1,0]
	v_pk_mul_f32 v[16:17], v[116:117], v[112:113]
	v_med3_f32 v5, v12, s52, v184
	v_med3_f32 v8, v13, s52, v184
	v_cvt_pk_fp8_f32 v7, v5, v8 op_sel:[0,0,1]
	v_pk_mul_f32 v[8:9], v[124:125], s[10:11] op_sel_hi:[1,0]
	v_or_b32_e32 v5, 16, v4
	v_exp_f32_e32 v8, v8
	v_exp_f32_e32 v9, v9
	v_mad_i64_i32 v[10:11], s[28:29], v5, s53, v[2:3]
	v_lshl_add_u64 v[10:11], v[10:11], 0, v[0:1]
	global_store_dwordx2 v[10:11], v[6:7], off nt
	v_pk_add_f32 v[6:7], v[8:9], 1.0 op_sel_hi:[1,0]
	v_pk_mul_f32 v[8:9], v[126:127], s[10:11] op_sel_hi:[1,0]
	v_rcp_f32_e32 v6, v6
	v_rcp_f32_e32 v7, v7
	v_exp_f32_e32 v8, v8
	v_exp_f32_e32 v9, v9
	v_pk_mul_f32 v[12:13], v[124:125], v[120:121]
	v_pk_mul_f32 v[10:11], v[126:127], v[122:123]
	v_pk_mul_f32 v[6:7], v[6:7], v[12:13]
	v_pk_add_f32 v[8:9], v[8:9], 1.0 op_sel_hi:[1,0]
	v_pk_mul_f32 v[12:13], v[116:117], s[10:11] op_sel_hi:[1,0]
	v_rcp_f32_e32 v8, v8
	v_rcp_f32_e32 v9, v9
	v_exp_f32_e32 v12, v12
	v_exp_f32_e32 v13, v13
	v_pk_mul_f32 v[6:7], v[6:7], s[12:13] op_sel_hi:[1,0]
	v_pk_mul_f32 v[8:9], v[8:9], v[10:11]
	v_med3_f32 v5, v6, s52, v184
	v_pk_add_f32 v[10:11], v[12:13], 1.0 op_sel_hi:[1,0]
	v_pk_mul_f32 v[12:13], v[118:119], s[10:11] op_sel_hi:[1,0]
	v_rcp_f32_e32 v10, v10
	v_exp_f32_e32 v12, v12
	v_exp_f32_e32 v13, v13
	v_rcp_f32_e32 v11, v11
	v_pk_mul_f32 v[8:9], v[8:9], s[12:13] op_sel_hi:[1,0]
	v_med3_f32 v7, v7, s52, v184
	v_pk_add_f32 v[12:13], v[12:13], 1.0 op_sel_hi:[1,0]
	v_pk_mul_f32 v[10:11], v[10:11], v[16:17]
	v_rcp_f32_e32 v12, v12
	v_rcp_f32_e32 v13, v13
	v_pk_mul_f32 v[10:11], v[10:11], s[12:13] op_sel_hi:[1,0]
	v_mov_b32_e32 v6, v165
	v_cvt_pk_fp8_f32 v6, v5, v7
	v_med3_f32 v5, v8, s52, v184
	v_med3_f32 v8, v9, s52, v184
	v_med3_f32 v9, v10, s52, v184
	v_med3_f32 v10, v11, s52, v184
	v_mov_b32_e32 v7, v165
	v_pk_mul_f32 v[14:15], v[118:119], v[114:115]
	v_cvt_pk_fp8_f32 v7, v9, v10
	v_pk_mul_f32 v[12:13], v[12:13], v[14:15]
	v_cvt_pk_fp8_f32 v6, v5, v8 op_sel:[0,0,1]
	v_pk_mul_f32 v[12:13], v[12:13], s[12:13] op_sel_hi:[1,0]
	v_pk_mul_f32 v[16:17], v[100:101], v[96:97]
	v_med3_f32 v5, v12, s52, v184
	v_med3_f32 v8, v13, s52, v184
	v_cvt_pk_fp8_f32 v7, v5, v8 op_sel:[0,0,1]
	v_pk_mul_f32 v[8:9], v[108:109], s[10:11] op_sel_hi:[1,0]
	v_or_b32_e32 v5, 32, v4
	v_exp_f32_e32 v8, v8
	v_exp_f32_e32 v9, v9
	v_mad_i64_i32 v[10:11], s[28:29], v5, s53, v[2:3]
	v_lshl_add_u64 v[10:11], v[10:11], 0, v[0:1]
	global_store_dwordx2 v[10:11], v[6:7], off nt
	v_pk_add_f32 v[6:7], v[8:9], 1.0 op_sel_hi:[1,0]
	v_pk_mul_f32 v[8:9], v[110:111], s[10:11] op_sel_hi:[1,0]
	v_rcp_f32_e32 v6, v6
	v_rcp_f32_e32 v7, v7
	v_exp_f32_e32 v8, v8
	v_exp_f32_e32 v9, v9
	v_pk_mul_f32 v[12:13], v[108:109], v[104:105]
	v_pk_mul_f32 v[10:11], v[110:111], v[106:107]
	v_pk_mul_f32 v[6:7], v[6:7], v[12:13]
	v_pk_add_f32 v[8:9], v[8:9], 1.0 op_sel_hi:[1,0]
	v_pk_mul_f32 v[12:13], v[100:101], s[10:11] op_sel_hi:[1,0]
	v_rcp_f32_e32 v8, v8
	v_rcp_f32_e32 v9, v9
	v_exp_f32_e32 v12, v12
	v_exp_f32_e32 v13, v13
	v_pk_mul_f32 v[6:7], v[6:7], s[12:13] op_sel_hi:[1,0]
	v_pk_mul_f32 v[8:9], v[8:9], v[10:11]
	v_med3_f32 v5, v6, s52, v184
	v_pk_add_f32 v[10:11], v[12:13], 1.0 op_sel_hi:[1,0]
	v_pk_mul_f32 v[12:13], v[102:103], s[10:11] op_sel_hi:[1,0]
	v_rcp_f32_e32 v10, v10
	v_exp_f32_e32 v12, v12
	v_exp_f32_e32 v13, v13
	v_rcp_f32_e32 v11, v11
	v_pk_mul_f32 v[8:9], v[8:9], s[12:13] op_sel_hi:[1,0]
	v_med3_f32 v7, v7, s52, v184
	v_pk_add_f32 v[12:13], v[12:13], 1.0 op_sel_hi:[1,0]
	v_pk_mul_f32 v[10:11], v[10:11], v[16:17]
	v_rcp_f32_e32 v12, v12
	v_rcp_f32_e32 v13, v13
	v_pk_mul_f32 v[10:11], v[10:11], s[12:13] op_sel_hi:[1,0]
	v_mov_b32_e32 v6, v165
	v_cvt_pk_fp8_f32 v6, v5, v7
	v_med3_f32 v5, v8, s52, v184
	v_med3_f32 v8, v9, s52, v184
	v_med3_f32 v9, v10, s52, v184
	v_med3_f32 v10, v11, s52, v184
	v_mov_b32_e32 v7, v165
	v_pk_mul_f32 v[14:15], v[102:103], v[98:99]
	v_cvt_pk_fp8_f32 v7, v9, v10
	v_pk_mul_f32 v[12:13], v[12:13], v[14:15]
	v_cvt_pk_fp8_f32 v6, v5, v8 op_sel:[0,0,1]
	v_pk_mul_f32 v[12:13], v[12:13], s[12:13] op_sel_hi:[1,0]
	v_pk_mul_f32 v[10:11], v[92:93], s[10:11] op_sel_hi:[1,0]
	v_med3_f32 v5, v12, s52, v184
	v_med3_f32 v8, v13, s52, v184
	v_cvt_pk_fp8_f32 v7, v5, v8 op_sel:[0,0,1]
	v_exp_f32_e32 v10, v10
	v_exp_f32_e32 v11, v11
	v_or_b32_e32 v5, 48, v4
	v_mad_i64_i32 v[8:9], s[28:29], v5, s53, v[2:3]
	v_lshl_add_u64 v[8:9], v[8:9], 0, v[0:1]
	global_store_dwordx2 v[8:9], v[6:7], off nt
	v_pk_add_f32 v[6:7], v[10:11], 1.0 op_sel_hi:[1,0]
	v_pk_mul_f32 v[8:9], v[94:95], s[10:11] op_sel_hi:[1,0]
	v_rcp_f32_e32 v6, v6
	v_rcp_f32_e32 v7, v7
	v_exp_f32_e32 v8, v8
	v_exp_f32_e32 v9, v9
	v_pk_mul_f32 v[12:13], v[92:93], v[88:89]
	v_pk_mul_f32 v[10:11], v[94:95], v[90:91]
	v_pk_mul_f32 v[6:7], v[6:7], v[12:13]
	v_pk_add_f32 v[8:9], v[8:9], 1.0 op_sel_hi:[1,0]
	v_pk_mul_f32 v[12:13], v[84:85], s[10:11] op_sel_hi:[1,0]
	v_rcp_f32_e32 v8, v8
	v_rcp_f32_e32 v9, v9
	v_exp_f32_e32 v12, v12
	v_exp_f32_e32 v13, v13
	v_pk_mul_f32 v[16:17], v[84:85], v[80:81]
	v_pk_mul_f32 v[8:9], v[8:9], v[10:11]
	v_pk_mul_f32 v[6:7], v[6:7], s[12:13] op_sel_hi:[1,0]
	v_pk_add_f32 v[10:11], v[12:13], 1.0 op_sel_hi:[1,0]
	v_pk_mul_f32 v[12:13], v[86:87], s[10:11] op_sel_hi:[1,0]
	v_rcp_f32_e32 v10, v10
	v_exp_f32_e32 v12, v12
	v_exp_f32_e32 v13, v13
	v_rcp_f32_e32 v11, v11
	v_pk_mul_f32 v[14:15], v[86:87], v[82:83]
	v_med3_f32 v7, v7, s52, v184
	v_pk_add_f32 v[12:13], v[12:13], 1.0 op_sel_hi:[1,0]
	v_pk_mul_f32 v[10:11], v[10:11], v[16:17]
	v_rcp_f32_e32 v12, v12
	v_rcp_f32_e32 v13, v13
	v_pk_mul_f32 v[10:11], v[10:11], s[12:13] op_sel_hi:[1,0]
	v_pk_mul_f32 v[8:9], v[8:9], s[12:13] op_sel_hi:[1,0]
	v_med3_f32 v10, v10, s52, v184
	v_pk_mul_f32 v[12:13], v[12:13], v[14:15]
	v_med3_f32 v14, v6, s52, v184
	v_mov_b32_e32 v6, v165
	v_cvt_pk_fp8_f32 v6, v14, v7
	v_med3_f32 v11, v11, s52, v184
	v_mov_b32_e32 v7, v165
	v_cvt_pk_fp8_f32 v7, v10, v11
	v_pk_mul_f32 v[12:13], v[12:13], s[12:13] op_sel_hi:[1,0]
	v_med3_f32 v8, v8, s52, v184
	v_med3_f32 v9, v9, s52, v184
	v_cvt_pk_fp8_f32 v6, v8, v9 op_sel:[0,0,1]
	v_med3_f32 v8, v12, s52, v184
	v_med3_f32 v9, v13, s52, v184
	v_cvt_pk_fp8_f32 v7, v8, v9 op_sel:[0,0,1]
	v_pk_mul_f32 v[8:9], v[76:77], s[10:11] op_sel_hi:[1,0]
	v_add_u32_e32 v5, 0x80, v4
	v_exp_f32_e32 v8, v8
	v_exp_f32_e32 v9, v9
	v_mad_i64_i32 v[10:11], s[28:29], v5, s53, v[2:3]
	v_lshl_add_u64 v[10:11], v[10:11], 0, v[0:1]
	global_store_dwordx2 v[10:11], v[6:7], off nt
	v_pk_add_f32 v[6:7], v[8:9], 1.0 op_sel_hi:[1,0]
	v_pk_mul_f32 v[8:9], v[78:79], s[10:11] op_sel_hi:[1,0]
	v_rcp_f32_e32 v6, v6
	v_rcp_f32_e32 v7, v7
	v_exp_f32_e32 v8, v8
	v_exp_f32_e32 v9, v9
	v_pk_mul_f32 v[12:13], v[76:77], v[72:73]
	v_pk_mul_f32 v[10:11], v[78:79], v[74:75]
	v_pk_mul_f32 v[6:7], v[6:7], v[12:13]
	v_pk_add_f32 v[8:9], v[8:9], 1.0 op_sel_hi:[1,0]
	v_pk_mul_f32 v[12:13], v[68:69], s[10:11] op_sel_hi:[1,0]
	v_rcp_f32_e32 v8, v8
	v_rcp_f32_e32 v9, v9
	v_exp_f32_e32 v12, v12
	v_exp_f32_e32 v13, v13
	v_pk_mul_f32 v[16:17], v[68:69], v[64:65]
	v_pk_mul_f32 v[8:9], v[8:9], v[10:11]
	v_pk_mul_f32 v[6:7], v[6:7], s[12:13] op_sel_hi:[1,0]
	v_pk_add_f32 v[10:11], v[12:13], 1.0 op_sel_hi:[1,0]
	v_pk_mul_f32 v[12:13], v[70:71], s[10:11] op_sel_hi:[1,0]
	v_rcp_f32_e32 v10, v10
	v_exp_f32_e32 v12, v12
	v_exp_f32_e32 v13, v13
	v_rcp_f32_e32 v11, v11
	v_pk_mul_f32 v[8:9], v[8:9], s[12:13] op_sel_hi:[1,0]
	v_med3_f32 v5, v6, s52, v184
	v_pk_add_f32 v[12:13], v[12:13], 1.0 op_sel_hi:[1,0]
	v_pk_mul_f32 v[10:11], v[10:11], v[16:17]
	v_rcp_f32_e32 v12, v12
	v_rcp_f32_e32 v13, v13
	v_pk_mul_f32 v[10:11], v[10:11], s[12:13] op_sel_hi:[1,0]
	v_med3_f32 v7, v7, s52, v184
	v_mov_b32_e32 v6, v165
	v_cvt_pk_fp8_f32 v6, v5, v7
	v_med3_f32 v5, v8, s52, v184
	v_med3_f32 v8, v9, s52, v184
	v_med3_f32 v9, v10, s52, v184
	v_med3_f32 v10, v11, s52, v184
	v_mov_b32_e32 v7, v165
	v_pk_mul_f32 v[14:15], v[70:71], v[66:67]
	v_cvt_pk_fp8_f32 v7, v9, v10
	v_pk_mul_f32 v[12:13], v[12:13], v[14:15]
	v_cvt_pk_fp8_f32 v6, v5, v8 op_sel:[0,0,1]
	v_pk_mul_f32 v[12:13], v[12:13], s[12:13] op_sel_hi:[1,0]
	v_pk_mul_f32 v[16:17], v[52:53], v[48:49]
	v_med3_f32 v5, v12, s52, v184
	v_med3_f32 v8, v13, s52, v184
	v_cvt_pk_fp8_f32 v7, v5, v8 op_sel:[0,0,1]
	v_pk_mul_f32 v[8:9], v[60:61], s[10:11] op_sel_hi:[1,0]
	v_add_u32_e32 v5, 0x90, v4
	v_exp_f32_e32 v8, v8
	v_exp_f32_e32 v9, v9
	v_mad_i64_i32 v[10:11], s[28:29], v5, s53, v[2:3]
	v_lshl_add_u64 v[10:11], v[10:11], 0, v[0:1]
	global_store_dwordx2 v[10:11], v[6:7], off nt
	v_pk_add_f32 v[6:7], v[8:9], 1.0 op_sel_hi:[1,0]
	v_pk_mul_f32 v[8:9], v[62:63], s[10:11] op_sel_hi:[1,0]
	v_rcp_f32_e32 v6, v6
	v_rcp_f32_e32 v7, v7
	v_exp_f32_e32 v8, v8
	v_exp_f32_e32 v9, v9
	v_pk_mul_f32 v[12:13], v[60:61], v[56:57]
	v_pk_mul_f32 v[10:11], v[62:63], v[58:59]
	v_pk_mul_f32 v[6:7], v[6:7], v[12:13]
	v_pk_add_f32 v[8:9], v[8:9], 1.0 op_sel_hi:[1,0]
	v_pk_mul_f32 v[12:13], v[52:53], s[10:11] op_sel_hi:[1,0]
	v_rcp_f32_e32 v8, v8
	v_rcp_f32_e32 v9, v9
	v_exp_f32_e32 v12, v12
	v_exp_f32_e32 v13, v13
	v_pk_mul_f32 v[6:7], v[6:7], s[12:13] op_sel_hi:[1,0]
	v_pk_mul_f32 v[8:9], v[8:9], v[10:11]
	v_med3_f32 v5, v6, s52, v184
	v_pk_add_f32 v[10:11], v[12:13], 1.0 op_sel_hi:[1,0]
	v_pk_mul_f32 v[12:13], v[54:55], s[10:11] op_sel_hi:[1,0]
	v_rcp_f32_e32 v10, v10
	v_exp_f32_e32 v12, v12
	v_exp_f32_e32 v13, v13
	v_rcp_f32_e32 v11, v11
	v_pk_mul_f32 v[8:9], v[8:9], s[12:13] op_sel_hi:[1,0]
	v_med3_f32 v7, v7, s52, v184
	v_pk_add_f32 v[12:13], v[12:13], 1.0 op_sel_hi:[1,0]
	v_pk_mul_f32 v[10:11], v[10:11], v[16:17]
	v_rcp_f32_e32 v12, v12
	v_rcp_f32_e32 v13, v13
	v_pk_mul_f32 v[10:11], v[10:11], s[12:13] op_sel_hi:[1,0]
	v_mov_b32_e32 v6, v165
	v_cvt_pk_fp8_f32 v6, v5, v7
	v_med3_f32 v5, v8, s52, v184
	v_med3_f32 v8, v9, s52, v184
	v_med3_f32 v9, v10, s52, v184
	v_med3_f32 v10, v11, s52, v184
	v_mov_b32_e32 v7, v165
	v_pk_mul_f32 v[14:15], v[54:55], v[50:51]
	v_cvt_pk_fp8_f32 v7, v9, v10
	v_pk_mul_f32 v[12:13], v[12:13], v[14:15]
	v_cvt_pk_fp8_f32 v6, v5, v8 op_sel:[0,0,1]
	v_pk_mul_f32 v[12:13], v[12:13], s[12:13] op_sel_hi:[1,0]
	v_pk_mul_f32 v[16:17], v[36:37], v[32:33]
	v_med3_f32 v5, v12, s52, v184
	v_med3_f32 v8, v13, s52, v184
	v_cvt_pk_fp8_f32 v7, v5, v8 op_sel:[0,0,1]
	v_pk_mul_f32 v[8:9], v[44:45], s[10:11] op_sel_hi:[1,0]
	v_add_u32_e32 v5, 0xa0, v4
	v_exp_f32_e32 v8, v8
	v_exp_f32_e32 v9, v9
	v_mad_i64_i32 v[10:11], s[28:29], v5, s53, v[2:3]
	v_lshl_add_u64 v[10:11], v[10:11], 0, v[0:1]
	global_store_dwordx2 v[10:11], v[6:7], off nt
	v_pk_add_f32 v[6:7], v[8:9], 1.0 op_sel_hi:[1,0]
	v_pk_mul_f32 v[8:9], v[46:47], s[10:11] op_sel_hi:[1,0]
	v_rcp_f32_e32 v6, v6
	v_rcp_f32_e32 v7, v7
	v_exp_f32_e32 v8, v8
	v_exp_f32_e32 v9, v9
	v_pk_mul_f32 v[12:13], v[44:45], v[40:41]
	v_pk_mul_f32 v[10:11], v[46:47], v[42:43]
	v_pk_mul_f32 v[6:7], v[6:7], v[12:13]
	v_pk_add_f32 v[8:9], v[8:9], 1.0 op_sel_hi:[1,0]
	v_pk_mul_f32 v[12:13], v[36:37], s[10:11] op_sel_hi:[1,0]
	v_rcp_f32_e32 v8, v8
	v_rcp_f32_e32 v9, v9
	v_exp_f32_e32 v12, v12
	v_exp_f32_e32 v13, v13
	v_pk_mul_f32 v[6:7], v[6:7], s[12:13] op_sel_hi:[1,0]
	v_pk_mul_f32 v[8:9], v[8:9], v[10:11]
	v_med3_f32 v5, v6, s52, v184
	v_pk_add_f32 v[10:11], v[12:13], 1.0 op_sel_hi:[1,0]
	v_pk_mul_f32 v[12:13], v[38:39], s[10:11] op_sel_hi:[1,0]
	v_rcp_f32_e32 v10, v10
	v_exp_f32_e32 v12, v12
	v_exp_f32_e32 v13, v13
	v_rcp_f32_e32 v11, v11
	v_pk_mul_f32 v[8:9], v[8:9], s[12:13] op_sel_hi:[1,0]
	v_med3_f32 v7, v7, s52, v184
	v_pk_add_f32 v[12:13], v[12:13], 1.0 op_sel_hi:[1,0]
	v_pk_mul_f32 v[10:11], v[10:11], v[16:17]
	v_rcp_f32_e32 v12, v12
	v_rcp_f32_e32 v13, v13
	v_pk_mul_f32 v[10:11], v[10:11], s[12:13] op_sel_hi:[1,0]
	v_mov_b32_e32 v6, v165
	v_cvt_pk_fp8_f32 v6, v5, v7
	v_med3_f32 v5, v8, s52, v184
	v_med3_f32 v8, v9, s52, v184
	v_med3_f32 v9, v10, s52, v184
	v_med3_f32 v10, v11, s52, v184
	v_mov_b32_e32 v7, v165
	v_pk_mul_f32 v[14:15], v[38:39], v[34:35]
	v_cvt_pk_fp8_f32 v7, v9, v10
	v_pk_mul_f32 v[12:13], v[12:13], v[14:15]
	v_cvt_pk_fp8_f32 v6, v5, v8 op_sel:[0,0,1]
	v_pk_mul_f32 v[12:13], v[12:13], s[12:13] op_sel_hi:[1,0]
	v_add_u32_e32 v4, 0xb0, v4
	v_med3_f32 v5, v12, s52, v184
	v_med3_f32 v8, v13, s52, v184
	v_cvt_pk_fp8_f32 v7, v5, v8 op_sel:[0,0,1]
	v_mad_i64_i32 v[2:3], s[28:29], v4, s53, v[2:3]
	v_lshl_add_u64 v[0:1], v[2:3], 0, v[0:1]
	s_andn2_b64 vcc, exec, s[0:1]
	s_mov_b64 s[0:1], -1
	global_store_dwordx2 v[0:1], v[6:7], off nt
	s_cbranch_vccnz .LBB0_1262
	s_andn2_b64 vcc, exec, s[4:5]
	s_cbranch_vccnz .LBB0_1261
	s_barrier
	s_branch .LBB0_1261
